# v3 + layer-1 w_out/w_gate transposes moved before the phase-6 barrier, handed out by atomic ticket
# baseline (speedup 1.0000x reference)
; #define LAS __attribute__((address_space(3)))
; template <bool REMAP = false>
; __device__ __forceinline__ void transpose_convert(LAS unsigned char* lds, const float* src, bf16_t* dst, int K, int N, int G, int bid) {
;     LAS float* tile = (LAS float*)lds;
;     const int tid = threadIdx.x, ntn = N / 64, ntiles = (K / 128) * ntn;
;     const int r0 = tid >> 4, c4 = tid & 15;
;     f32x4 v[4];
;     if (bid < ntiles) { const int k0 = (bid / ntn) * 128, n0 = (bid % ntn) * 64;
; #pragma unroll
;         for (int i = 0; i < 4; ++i) v[i] = __builtin_nontemporal_load((const f32x4*)(src + (size_t)(k0 + r0 + 32 * i) * N + n0 + c4 * 4)); }
;     for (int t = bid; t < ntiles; t += G) {
;         const int k0 = (t / ntn) * 128, n0 = (t % ntn) * 64;
;         asm volatile("s_waitcnt lgkmcnt(0)" ::: "memory"); __builtin_amdgcn_s_barrier(); asm volatile("" ::: "memory");
; #pragma unroll
;         for (int i = 0; i < 4; ++i) {
; #pragma unroll
;             for (int j = 0; j < 4; ++j) tile[(r0 + 32 * i) * 65 + c4 * 4 + j] = v[i][j]; }
;         asm volatile("s_waitcnt lgkmcnt(0)" ::: "memory"); __builtin_amdgcn_s_barrier(); asm volatile("" ::: "memory");
;         if (t + G < ntiles) { const int k1 = ((t + G) / ntn) * 128, n1 = ((t + G) % ntn) * 64;
; #pragma unroll
;             for (int i = 0; i < 4; ++i) v[i] = __builtin_nontemporal_load((const f32x4*)(src + (size_t)(k1 + r0 + 32 * i) * N + n1 + c4 * 4)); }
; __global__ void __launch_bounds__(NTHREADS, 2) mk_fwd(Params P) {
;     ...
;         transpose_convert(lds, P.w_out + (size_t)2048 * 2048, WOUT1, 2048, 2048, G, bid);
;         transpose_convert(lds, P.w_gate + (size_t)2048 * 2048, WG1, 2048, 2048, G, bid);
.LBB0_570:
	s_waitcnt vmcnt(0)
	s_barrier
	s_mov_b64 s[100:101], s[16:17]
	s_add_u32 s24, s40, 0x2000000
	s_addc_u32 s25, s41, 0
	s_add_u32 s22, s40, 0x2800000
	s_addc_u32 s23, s41, 0
	s_movk_i32 s98, 0x100
	v_mov_b32_e32 v46, 0x20008
.Ldyn7_top:
	s_waitcnt vmcnt(0) lgkmcnt(0)
	s_barrier
	s_add_u32 s10, s54, 0xa000
	s_addc_u32 s11, s55, 0
	s_and_saveexec_b64 s[18:19], s[12:13]
	s_cbranch_execz .Ldyn7_nofetch
	v_mov_b32_e32 v0, 0
	v_mov_b32_e32 v1, 1
	global_atomic_add v1, v0, v1, s[10:11] sc0
	s_waitcnt vmcnt(0)
	ds_write_b32 v46, v1
.Ldyn7_nofetch:
	s_or_b64 exec, exec, s[18:19]
	s_waitcnt lgkmcnt(0)
	s_barrier
	ds_read_b32 v1, v46
	s_waitcnt lgkmcnt(0)
	v_readfirstlane_b32 s99, v1
	s_nop 3
	s_cmp_gt_u32 s99, 0xff
	s_cbranch_scc1 .Ldyn7_exit
	s_cmpk_lt_i32 s99, 0x200
	s_cselect_b64 s[4:5], -1, 0
	s_cmpk_gt_i32 s99, 0x1ff
	v_lshl_add_u32 v20, v214, 2, 0
	s_cbranch_scc1 .LBB0_629
	s_add_u32 s6, s44, 0x1000000
	s_addc_u32 s7, s45, 0
	s_ashr_i32 s8, s99, 31
	s_lshr_b32 s8, s8, 27
	s_add_i32 s8, s99, s8
	s_lshl_b32 s9, s8, 2
	s_and_b32 s8, s8, 0x3ffffe0
	s_sub_i32 s8, s99, s8
	s_and_b32 s9, s9, 0xffffff80
	s_lshl_b32 s8, s8, 6
	s_waitcnt vmcnt(0)
	v_or_b32_e32 v8, s9, v214
	s_ashr_i32 s9, s8, 31
	s_lshl_b64 s[8:9], s[8:9], 2
	v_and_b32_e32 v24, 15, v164
	s_add_u32 s8, s6, s8
	s_addc_u32 s9, s7, s9
	v_lshlrev_b32_e32 v18, 4, v24
	v_mov_b32_e32 v19, 0
	v_ashrrev_i32_e32 v9, 31, v8
	v_lshl_add_u64 v[10:11], s[8:9], 0, v[18:19]
	v_lshlrev_b64 v[0:1], 13, v[8:9]
	v_lshl_add_u64 v[12:13], v[10:11], 0, v[0:1]
	s_mov_b32 s10, 0x40000
	v_or_b32_e32 v8, 64, v8
	v_add_co_u32_e32 v14, vcc, s10, v12
	v_ashrrev_i32_e32 v9, 31, v8
	s_nop 0
	v_addc_co_u32_e32 v15, vcc, 0, v13, vcc
	v_lshlrev_b64 v[8:9], 13, v[8:9]
	s_mov_b32 s11, 0xc0000
	v_lshl_add_u64 v[16:17], v[10:11], 0, v[8:9]
	v_add_co_u32_e32 v22, vcc, s11, v12
	global_load_dwordx4 v[0:3], v[12:13], off nt
	global_load_dwordx4 v[4:7], v[14:15], off nt
	v_addc_co_u32_e32 v23, vcc, 0, v13, vcc
	global_load_dwordx4 v[8:11], v[16:17], off nt
	global_load_dwordx4 v[12:15], v[22:23], off nt
	v_add_u32_e32 v21, 0x200, v164
	v_add_u32_e32 v22, 0, v18
	v_lshrrev_b32_e32 v21, 4, v21
	v_mul_u32_u24_e32 v23, 0x104, v214
	v_lshl_add_u32 v27, v21, 2, 0
	v_mul_u32_u24_e32 v28, 0x820, v24
	v_add_u32_e32 v22, v22, v23
	v_lshl_add_u64 v[16:17], s[6:7], 0, v[18:19]
	v_lshl_add_u64 v[18:19], s[24:25], 0, v[18:19]
	s_lshl_b32 s17, s99, 6
	s_lshl_b32 s16, s98, 6
	v_add_u32_e32 v23, 0x2080, v22
	v_add_u32_e32 v24, 0x2088, v22
	v_add_u32_e32 v25, 0x4100, v22
	v_add_u32_e32 v26, v20, v28
	v_add_u32_e32 v27, v27, v28
	v_add_u32_e32 v28, 0x4108, v22
	v_add_u32_e32 v29, 0x6180, v22
	s_mov_b32 s18, s99
	s_branch .LBB0_625

; template <bool REMAP = false>
; __device__ __forceinline__ void transpose_convert(LAS unsigned char* lds, const float* src, bf16_t* dst, int K, int N, int G, int bid) {
;     ...
;     for (int t = bid; t < ntiles; t += G) {
;         const int k0 = (t / ntn) * 128, n0 = (t % ntn) * 64;
;         asm volatile("s_waitcnt lgkmcnt(0)" ::: "memory"); __builtin_amdgcn_s_barrier(); asm volatile("" ::: "memory");
; #pragma unroll
;         for (int i = 0; i < 4; ++i) {
; #pragma unroll
;             for (int j = 0; j < 4; ++j) tile[(r0 + 32 * i) * 65 + c4 * 4 + j] = v[i][j]; }
;         asm volatile("s_waitcnt lgkmcnt(0)" ::: "memory"); __builtin_amdgcn_s_barrier(); asm volatile("" ::: "memory");
;         if (t + G < ntiles) { const int k1 = ((t + G) / ntn) * 128, n1 = ((t + G) % ntn) * 64;
; #pragma unroll
;             for (int i = 0; i < 4; ++i) v[i] = __builtin_nontemporal_load((const f32x4*)(src + (size_t)(k1 + r0 + 32 * i) * N + n1 + c4 * 4)); }
.LBB0_625:
	s_nop 0
	v_add_u32_e32 v30, 0x6188, v22
	s_waitcnt lgkmcnt(0)
	s_barrier
	s_waitcnt vmcnt(3)
	ds_write2_b32 v22, v0, v1 offset1:1
	ds_write2_b32 v22, v2, v3 offset0:2 offset1:3
	s_waitcnt vmcnt(2)
	ds_write2_b32 v23, v4, v5 offset1:1
	ds_write2_b32 v24, v6, v7 offset1:1
	s_waitcnt vmcnt(1)
	ds_write2_b32 v25, v8, v9 offset1:1
	ds_write2_b32 v28, v10, v11 offset1:1
	s_waitcnt vmcnt(0)
	ds_write2_b32 v29, v12, v13 offset1:1
	ds_write2_b32 v30, v14, v15 offset1:1
	s_waitcnt lgkmcnt(0)
	s_barrier
	s_add_i32 s19, s18, s98
	s_cmpk_gt_i32 s19, 0x1ff
	s_cselect_b64 s[6:7], -1, 0
	s_cmpk_lt_i32 s19, 0x200
	s_mov_b64 s[8:9], -1
	s_cbranch_scc1 .LBB0_627
	s_add_i32 s28, s17, s16
	s_mov_b64 s[8:9], 0

; #define LAS __attribute__((address_space(3)))
; template <bool REMAP = false>
; __device__ __forceinline__ void transpose_convert(LAS unsigned char* lds, const float* src, bf16_t* dst, int K, int N, int G, int bid) {
;     LAS float* tile = (LAS float*)lds;
;     const int tid = threadIdx.x, ntn = N / 64, ntiles = (K / 128) * ntn;
;     const int r0 = tid >> 4, c4 = tid & 15;
;     f32x4 v[4];
;     if (bid < ntiles) { const int k0 = (bid / ntn) * 128, n0 = (bid % ntn) * 64;
; #pragma unroll
;         for (int i = 0; i < 4; ++i) v[i] = __builtin_nontemporal_load((const f32x4*)(src + (size_t)(k0 + r0 + 32 * i) * N + n0 + c4 * 4)); }
;     for (int t = bid; t < ntiles; t += G) {
;         const int k0 = (t / ntn) * 128, n0 = (t % ntn) * 64;
; __global__ void __launch_bounds__(NTHREADS, 2) mk_fwd(Params P) {
;     ...
;         transpose_convert(lds, P.w_gate + (size_t)2048 * 2048, WG1, 2048, 2048, G, bid);
.LBB0_629:
	s_andn2_b64 vcc, exec, s[4:5]
	s_waitcnt vmcnt(0) lgkmcnt(0)
	s_barrier
	s_cbranch_vccnz .Ldyn7_top
	s_add_u32 s4, s50, 0x1000000
	s_addc_u32 s5, s51, 0
	s_ashr_i32 s6, s99, 31
	s_lshr_b32 s6, s6, 27
	s_add_i32 s6, s99, s6
	s_lshl_b32 s7, s6, 2
	s_and_b32 s6, s6, 0x3ffffe0
	s_sub_i32 s6, s99, s6
	s_and_b32 s7, s7, 0xffffff80
	s_lshl_b32 s6, s6, 6
	v_or_b32_e32 v8, s7, v214
	s_ashr_i32 s7, s6, 31
	s_lshl_b64 s[6:7], s[6:7], 2
	v_and_b32_e32 v24, 15, v164
	s_add_u32 s6, s4, s6
	s_addc_u32 s7, s5, s7
	v_lshlrev_b32_e32 v18, 4, v24
	v_mov_b32_e32 v19, 0
	v_ashrrev_i32_e32 v9, 31, v8
	v_lshl_add_u64 v[10:11], s[6:7], 0, v[18:19]
	v_lshlrev_b64 v[0:1], 13, v[8:9]
	v_lshl_add_u64 v[12:13], v[10:11], 0, v[0:1]
	s_mov_b32 s8, 0x40000
	v_or_b32_e32 v8, 64, v8
	v_add_co_u32_e32 v14, vcc, s8, v12
	v_ashrrev_i32_e32 v9, 31, v8
	s_nop 0
	v_addc_co_u32_e32 v15, vcc, 0, v13, vcc
	v_lshlrev_b64 v[8:9], 13, v[8:9]
	s_mov_b32 s9, 0xc0000
	v_lshl_add_u64 v[16:17], v[10:11], 0, v[8:9]
	v_add_co_u32_e32 v22, vcc, s9, v12
	global_load_dwordx4 v[0:3], v[12:13], off nt
	global_load_dwordx4 v[4:7], v[14:15], off nt
	v_addc_co_u32_e32 v23, vcc, 0, v13, vcc
	global_load_dwordx4 v[8:11], v[16:17], off nt
	global_load_dwordx4 v[12:15], v[22:23], off nt
	v_add_u32_e32 v21, 0x200, v164
	v_add_u32_e32 v22, 0, v18
	v_lshrrev_b32_e32 v21, 4, v21
	v_mul_u32_u24_e32 v23, 0x104, v214
	v_lshl_add_u32 v26, v21, 2, 0
	v_mul_u32_u24_e32 v27, 0x820, v24
	v_add_u32_e32 v22, v22, v23
	v_lshl_add_u64 v[16:17], s[4:5], 0, v[18:19]
	v_lshl_add_u64 v[18:19], s[22:23], 0, v[18:19]
	s_lshl_b32 s11, s99, 6
	s_lshl_b32 s10, s98, 6
	v_add_u32_e32 v23, 0x2080, v22
	v_add_u32_e32 v24, 0x2088, v22
	v_add_u32_e32 v25, 0x4100, v22
	v_add_u32_e32 v20, v20, v27
	v_add_u32_e32 v26, v26, v27
	v_add_u32_e32 v27, 0x4108, v22
	v_add_u32_e32 v28, 0x6180, v22
	s_mov_b32 s16, s99
	s_branch .LBB0_632

; template <bool REMAP = false>
; __device__ __forceinline__ void transpose_convert(LAS unsigned char* lds, const float* src, bf16_t* dst, int K, int N, int G, int bid) {
;     ...
;     for (int t = bid; t < ntiles; t += G) {
;         const int k0 = (t / ntn) * 128, n0 = (t % ntn) * 64;
;         asm volatile("s_waitcnt lgkmcnt(0)" ::: "memory"); __builtin_amdgcn_s_barrier(); asm volatile("" ::: "memory");
; #pragma unroll
;         for (int i = 0; i < 4; ++i) {
; #pragma unroll
;             for (int j = 0; j < 4; ++j) tile[(r0 + 32 * i) * 65 + c4 * 4 + j] = v[i][j]; }
;         asm volatile("s_waitcnt lgkmcnt(0)" ::: "memory"); __builtin_amdgcn_s_barrier(); asm volatile("" ::: "memory");
;         if (t + G < ntiles) { const int k1 = ((t + G) / ntn) * 128, n1 = ((t + G) % ntn) * 64;
; #pragma unroll
;             for (int i = 0; i < 4; ++i) v[i] = __builtin_nontemporal_load((const f32x4*)(src + (size_t)(k1 + r0 + 32 * i) * N + n1 + c4 * 4)); }
.LBB0_632:
	v_add_u32_e32 v29, 0x6188, v22
	s_waitcnt lgkmcnt(0)
	s_barrier
	s_waitcnt vmcnt(3)
	ds_write2_b32 v22, v0, v1 offset1:1
	ds_write2_b32 v22, v2, v3 offset0:2 offset1:3
	s_waitcnt vmcnt(2)
	ds_write2_b32 v23, v4, v5 offset1:1
	ds_write2_b32 v24, v6, v7 offset1:1
	s_waitcnt vmcnt(1)
	ds_write2_b32 v25, v8, v9 offset1:1
	ds_write2_b32 v27, v10, v11 offset1:1
	s_waitcnt vmcnt(0)
	ds_write2_b32 v28, v12, v13 offset1:1
	ds_write2_b32 v29, v14, v15 offset1:1
	s_waitcnt lgkmcnt(0)
	s_barrier
	s_add_i32 s17, s16, s98
	s_cmpk_gt_i32 s17, 0x1ff
	s_cselect_b64 s[4:5], -1, 0
	s_cmpk_lt_i32 s17, 0x200
	s_mov_b64 s[6:7], -1
	s_cbranch_scc1 .LBB0_634
	s_add_i32 s18, s11, s10
	s_mov_b64 s[6:7], 0

; __global__ void __launch_bounds__(NTHREADS, 2) mk_fwd(Params P) {
;     ...
;         transpose_convert(lds, P.w_out + (size_t)2048 * 2048, WOUT1, 2048, 2048, G, bid);
;         transpose_convert(lds, P.w_gate + (size_t)2048 * 2048, WG1, 2048, 2048, G, bid);
.Ldyn7_exit:
	s_mov_b64 s[16:17], s[100:101]

; __device__ __forceinline__ void attn_phase(LAS unsigned char* lds, const bf16_t* Q, const bf16_t* Kb, const bf16_t* VT, const bf16_t* Z, const float* kpart, bf16_t* Y, int G, int bid) {
;     ...
;     const int tid = threadIdx.x, wid = __builtin_amdgcn_readfirstlane(tid >> 6), lane = tid & 63, qr = lane & 31, hh = lane >> 5;
;     const float NEG = -__builtin_inff();
;     for (int pair = bid; pair < 256; pair += G) {
;         const int bh = pair >> 2, jp = pair & 3, b = bh >> 4, h = bh & 15;
;         for (int half = 0; half < 2; ++half) {
;             const int own = half == 0 ? 7 - jp : jp;
;             const int q0 = own * 256 + wid * 32;
;             const size_t qoff = (size_t)(b * SEQ + q0 + qr) * DM + h * 128;
;             bf16x8 Qf[8];
; #pragma unroll
;             for (int ks = 0; ks < 8; ++ks) Qf[ks] = *(const bf16x8*)(Q + qoff + ks * 16 + hh * 8);
;             unsigned selmask = (1u << own) - 1u;
; __global__ void __launch_bounds__(NTHREADS, 2) mk_fwd(Params P) {
;     ...
;     if (IN(7)) {
;         transpose_convert(lds, P.w_out + (size_t)2048 * 2048, WOUT1, 2048, 2048, G, bid);
;         transpose_convert(lds, P.w_gate + (size_t)2048 * 2048, WG1, 2048, 2048, G, bid);
;     }
;     if (IN(7)) attn_phase(lds, Qb, Kb, VTb, Zb, KPART, Y1, G, bid);
.LBB0_621:
	s_add_u32 s24, s40, 0x2000000
	s_addc_u32 s25, s41, 0
	s_add_u32 s22, s40, 0x2800000
	s_addc_u32 s23, s41, 0
	s_cmp_lt_i32 s42, 8
	s_cselect_b64 s[6:7], -1, 0
	s_and_b64 s[26:27], s[6:7], s[4:5]
	s_andn2_b64 vcc, exec, s[26:27]
	s_cbranch_vccnz .LBB0_680
.LBB0_636:
	s_cmpk_gt_i32 s2, 0xff
	v_readfirstlane_b32 s4, v164
	s_barrier
	s_cbranch_scc1 .LBB0_679
	s_waitcnt vmcnt(5)
	v_lshlrev_b32_e32 v3, 4, v164
	v_and_b32_e32 v153, 31, v164
	v_bfe_u32 v1, v164, 5, 1
	s_waitcnt vmcnt(4)
	v_and_b32_e32 v4, 0xf0, v3
	v_lshlrev_b32_e32 v144, 4, v1
	v_add_u32_e32 v157, 0, v4
	v_and_b32_e32 v4, 0x70, v3
	v_mul_u32_u24_e32 v3, 0x110, v153
	v_lshlrev_b32_e32 v0, 3, v1
	v_mov_b32_e32 v145, 0
	v_cmp_eq_u32_e64 s[6:7], 0, v1
	v_add3_u32 v161, 0, v3, v144
	v_lshlrev_b32_e32 v148, 2, v1
	v_lshlrev_b32_e32 v1, 7, v153
	s_add_u32 s28, s40, 0xc000000
	v_sub_u32_e32 v163, v161, v1
	v_mov_b32_e32 v5, v145
	v_lshlrev_b32_e32 v1, 8, v164
	s_addc_u32 s29, s41, 0
	s_lshr_b32 s4, s4, 1
	v_add_u32_e32 v159, 0, v4
	v_lshl_add_u64 v[150:151], s[0:1], 0, v[4:5]
	v_and_b32_e32 v4, 0x3f800, v1
	v_add_u32_e32 v1, 0x200, v164
	s_and_b32 s69, s4, 0x7fffffe0
	v_lshlrev_b32_e32 v2, 3, v164
	v_lshlrev_b32_e32 v3, 8, v1
	v_and_b32_e32 v2, 0x78, v2
	v_lshrrev_b32_e32 v165, 4, v1
	v_and_b32_e32 v6, 0x7f800, v3
	v_lshrrev_b32_e32 v3, 3, v164
	v_lshrrev_b32_e32 v1, 3, v1
	s_cmp_lt_u32 s69, 63
	v_lshlrev_b32_e32 v184, 2, v0
	v_mbcnt_lo_u32_b32 v0, -1, 0
	v_lshl_add_u64 v[146:147], s[14:15], 0, v[144:145]
	v_cmp_gt_u32_e64 s[4:5], 8, v153
	v_lshlrev_b32_e32 v155, 1, v153
	s_mov_b32 s31, 0
	v_or_b32_e32 v152, 0x60, v148
	v_mul_u32_u24_e32 v167, 0x110, v214
	v_mul_u32_u24_e32 v169, 0x90, v3
	v_mul_u32_u24_e32 v171, 0x110, v165
	v_mul_u32_u24_e32 v173, 0x90, v1
	v_mov_b32_e32 v149, v145
	v_or_b32_e32 v154, 8, v148
	v_or_b32_e32 v156, 16, v148
	v_or_b32_e32 v158, 24, v148
	v_or_b32_e32 v160, 32, v148
	v_or_b32_e32 v162, 40, v148
	v_or_b32_e32 v166, 48, v148
	v_or_b32_e32 v168, 56, v148
	v_or_b32_e32 v170, 64, v148
	v_or_b32_e32 v172, 0x48, v148
	v_or_b32_e32 v174, 0x50, v148
	v_or_b32_e32 v176, 0x58, v148
	v_or_b32_e32 v178, 0x68, v148
	v_or_b32_e32 v180, 0x70, v148
	v_or_b32_e32 v182, 0x78, v148
	s_cselect_b64 s[36:37], -1, 0
	v_lshlrev_b32_e32 v186, 1, v2
	s_mov_b64 s[44:45], 0x2000
	s_mov_b64 s[50:51], 0x2040
	s_mov_b64 s[56:57], 0x2080
	s_mov_b64 s[58:59], 0x20c0
	s_mov_b64 s[60:61], 0x2100
	s_mov_b64 s[62:63], 0x2140
	s_mov_b64 s[64:65], 0x2180
	s_mov_b64 s[66:67], 0x21c0
	s_mov_b32 s68, 0x3b800000
	s_mov_b32 s72, 0xff800000
	v_lshlrev_b32_e32 v144, 1, v4
	v_lshlrev_b32_e32 v188, 1, v6
	v_mbcnt_hi_u32_b32 v175, -1, v0
	v_mov_b32_e32 v185, v145
	v_mov_b32_e32 v187, v145
	v_mov_b32_e32 v177, 0xff800000
	s_mov_b32 s73, s2
	s_branch .LBB0_639
